# att23 = att14 + nt (non-temporal) hint on the 32 write-once f32 output stores of the fused final norm
# baseline (speedup 1.0000x reference)
.LBB0_925:
	global_load_dword v144, v[112:113], off sc1
	v_lshlrev_b64 v[146:147], 12, v[216:217]
	v_lshl_add_u64 v[146:147], s[20:21], 0, v[146:147]
	s_and_b64 vcc, exec, s[6:7]
	s_mov_b64 s[0:1], -1
	s_waitcnt vmcnt(0)
	v_fmamk_f32 v144, v144, 0x3a800000, v226
	v_rsq_f32_e32 v148, v144
	v_lshlrev_b64 v[144:145], 2, v[214:215]
	v_lshl_add_u64 v[150:151], v[146:147], 0, v[144:145]
	v_pk_mul_f32 v[146:147], v[218:219], v[148:149] op_sel_hi:[1,0]
	v_pk_mul_f32 v[126:127], v[126:127], v[148:149] op_sel_hi:[1,0]
	v_pk_mul_f32 v[124:125], v[124:125], v[148:149] op_sel_hi:[1,0]
	v_pk_mul_f32 v[122:123], v[122:123], v[148:149] op_sel_hi:[1,0]
	v_pk_mul_f32 v[152:153], v[120:121], v[148:149] op_sel_hi:[1,0]
	v_pk_mul_f32 v[154:155], v[118:119], v[148:149] op_sel_hi:[1,0]
	v_pk_mul_f32 v[156:157], v[116:117], v[148:149] op_sel_hi:[1,0]
	v_pk_mul_f32 v[148:149], v[114:115], v[148:149] op_sel_hi:[1,0]
	v_pk_mul_f32 v[116:117], v[6:7], v[126:127]
	v_pk_mul_f32 v[114:115], v[4:5], v[146:147]
	v_pk_mul_f32 v[120:121], v[2:3], v[122:123]
	v_pk_mul_f32 v[118:119], v[0:1], v[124:125]
	v_pk_mul_f32 v[124:125], v[14:15], v[154:155]
	v_pk_mul_f32 v[122:123], v[12:13], v[152:153]
	v_pk_mul_f32 v[148:149], v[10:11], v[148:149]
	v_pk_mul_f32 v[146:147], v[8:9], v[156:157]
	global_store_dwordx4 v[150:151], v[114:117], off nt
	global_store_dwordx4 v[150:151], v[118:121], off offset:16 nt
	global_store_dwordx4 v[150:151], v[122:125], off offset:512 nt
	global_store_dwordx4 v[150:151], v[146:149], off offset:528 nt
	global_load_dword v114, v[176:177], off sc1
	v_lshlrev_b64 v[116:117], 12, v[212:213]
	v_lshl_add_u64 v[116:117], s[20:21], 0, v[116:117]
	v_lshl_add_u64 v[116:117], v[116:117], 0, v[144:145]
	s_waitcnt vmcnt(0)
	v_fmamk_f32 v114, v114, 0x3a800000, v226
	v_rsq_f32_e32 v114, v114
	s_nop 0
	v_pk_mul_f32 v[108:109], v[108:109], v[114:115] op_sel_hi:[1,0]
	v_pk_mul_f32 v[110:111], v[110:111], v[114:115] op_sel_hi:[1,0]
	v_pk_mul_f32 v[104:105], v[104:105], v[114:115] op_sel_hi:[1,0]
	v_pk_mul_f32 v[106:107], v[106:107], v[114:115] op_sel_hi:[1,0]
	v_pk_mul_f32 v[118:119], v[100:101], v[114:115] op_sel_hi:[1,0]
	v_pk_mul_f32 v[120:121], v[102:103], v[114:115] op_sel_hi:[1,0]
	v_pk_mul_f32 v[122:123], v[96:97], v[114:115] op_sel_hi:[1,0]
	v_pk_mul_f32 v[114:115], v[98:99], v[114:115] op_sel_hi:[1,0]
	v_pk_mul_f32 v[98:99], v[6:7], v[110:111]
	v_pk_mul_f32 v[96:97], v[4:5], v[108:109]
	v_pk_mul_f32 v[102:103], v[2:3], v[106:107]
	v_pk_mul_f32 v[100:101], v[0:1], v[104:105]
	v_pk_mul_f32 v[106:107], v[14:15], v[120:121]
	v_pk_mul_f32 v[104:105], v[12:13], v[118:119]
	v_pk_mul_f32 v[110:111], v[10:11], v[114:115]
	v_pk_mul_f32 v[108:109], v[8:9], v[122:123]
	global_store_dwordx4 v[116:117], v[96:99], off nt
	global_store_dwordx4 v[116:117], v[100:103], off offset:16 nt
	global_store_dwordx4 v[116:117], v[104:107], off offset:512 nt
	global_store_dwordx4 v[116:117], v[108:111], off offset:528 nt
	global_load_dword v96, v[168:169], off sc1
	v_lshlrev_b64 v[98:99], 12, v[210:211]
	v_lshl_add_u64 v[98:99], s[20:21], 0, v[98:99]
	v_lshl_add_u64 v[98:99], v[98:99], 0, v[144:145]
	s_waitcnt vmcnt(0)
	v_fmamk_f32 v96, v96, 0x3a800000, v226
	v_rsq_f32_e32 v96, v96
	s_nop 0
	v_pk_mul_f32 v[92:93], v[92:93], v[96:97] op_sel_hi:[1,0]
	v_pk_mul_f32 v[94:95], v[94:95], v[96:97] op_sel_hi:[1,0]
	v_pk_mul_f32 v[88:89], v[88:89], v[96:97] op_sel_hi:[1,0]
	v_pk_mul_f32 v[90:91], v[90:91], v[96:97] op_sel_hi:[1,0]
	v_pk_mul_f32 v[100:101], v[84:85], v[96:97] op_sel_hi:[1,0]
	v_pk_mul_f32 v[102:103], v[86:87], v[96:97] op_sel_hi:[1,0]
	v_pk_mul_f32 v[104:105], v[80:81], v[96:97] op_sel_hi:[1,0]
	v_pk_mul_f32 v[96:97], v[82:83], v[96:97] op_sel_hi:[1,0]
	v_pk_mul_f32 v[82:83], v[6:7], v[94:95]
	v_pk_mul_f32 v[80:81], v[4:5], v[92:93]
	v_pk_mul_f32 v[86:87], v[2:3], v[90:91]
	v_pk_mul_f32 v[84:85], v[0:1], v[88:89]
	v_pk_mul_f32 v[90:91], v[14:15], v[102:103]
	v_pk_mul_f32 v[88:89], v[12:13], v[100:101]
	v_pk_mul_f32 v[94:95], v[10:11], v[96:97]
	v_pk_mul_f32 v[92:93], v[8:9], v[104:105]
	global_store_dwordx4 v[98:99], v[80:83], off nt
	global_store_dwordx4 v[98:99], v[84:87], off offset:16 nt
	global_store_dwordx4 v[98:99], v[88:91], off offset:512 nt
	global_store_dwordx4 v[98:99], v[92:95], off offset:528 nt
	global_load_dword v80, v[160:161], off sc1
	v_lshlrev_b64 v[82:83], 12, v[208:209]
	v_lshl_add_u64 v[82:83], s[20:21], 0, v[82:83]
	v_lshl_add_u64 v[82:83], v[82:83], 0, v[144:145]
	s_waitcnt vmcnt(0)
	v_fmamk_f32 v80, v80, 0x3a800000, v226
	v_rsq_f32_e32 v80, v80
	s_nop 0
	v_pk_mul_f32 v[76:77], v[76:77], v[80:81] op_sel_hi:[1,0]
	v_pk_mul_f32 v[78:79], v[78:79], v[80:81] op_sel_hi:[1,0]
	v_pk_mul_f32 v[72:73], v[72:73], v[80:81] op_sel_hi:[1,0]
	v_pk_mul_f32 v[74:75], v[74:75], v[80:81] op_sel_hi:[1,0]
	v_pk_mul_f32 v[84:85], v[68:69], v[80:81] op_sel_hi:[1,0]
	v_pk_mul_f32 v[86:87], v[70:71], v[80:81] op_sel_hi:[1,0]
	v_pk_mul_f32 v[88:89], v[64:65], v[80:81] op_sel_hi:[1,0]
	v_pk_mul_f32 v[80:81], v[66:67], v[80:81] op_sel_hi:[1,0]
	v_pk_mul_f32 v[66:67], v[6:7], v[78:79]
	v_pk_mul_f32 v[64:65], v[4:5], v[76:77]
	v_pk_mul_f32 v[70:71], v[2:3], v[74:75]
	v_pk_mul_f32 v[68:69], v[0:1], v[72:73]
	v_pk_mul_f32 v[74:75], v[14:15], v[86:87]
	v_pk_mul_f32 v[72:73], v[12:13], v[84:85]
	v_pk_mul_f32 v[78:79], v[10:11], v[80:81]
	v_pk_mul_f32 v[76:77], v[8:9], v[88:89]
	global_store_dwordx4 v[82:83], v[64:67], off nt
	global_store_dwordx4 v[82:83], v[68:71], off offset:16 nt
	global_store_dwordx4 v[82:83], v[72:75], off offset:512 nt
	global_store_dwordx4 v[82:83], v[76:79], off offset:528 nt
	global_load_dword v64, v[112:113], off offset:512 sc1
	v_lshlrev_b64 v[66:67], 12, v[206:207]
	v_lshl_add_u64 v[66:67], s[20:21], 0, v[66:67]
	v_lshl_add_u64 v[66:67], v[66:67], 0, v[144:145]
	s_waitcnt vmcnt(0)
	v_fmamk_f32 v64, v64, 0x3a800000, v226
	v_rsq_f32_e32 v64, v64
	s_nop 0
	v_pk_mul_f32 v[60:61], v[60:61], v[64:65] op_sel_hi:[1,0]
	v_pk_mul_f32 v[62:63], v[62:63], v[64:65] op_sel_hi:[1,0]
	v_pk_mul_f32 v[56:57], v[56:57], v[64:65] op_sel_hi:[1,0]
	v_pk_mul_f32 v[58:59], v[58:59], v[64:65] op_sel_hi:[1,0]
	v_pk_mul_f32 v[68:69], v[52:53], v[64:65] op_sel_hi:[1,0]
	v_pk_mul_f32 v[70:71], v[54:55], v[64:65] op_sel_hi:[1,0]
	v_pk_mul_f32 v[72:73], v[48:49], v[64:65] op_sel_hi:[1,0]
	v_pk_mul_f32 v[64:65], v[50:51], v[64:65] op_sel_hi:[1,0]
	v_pk_mul_f32 v[50:51], v[6:7], v[62:63]
	v_pk_mul_f32 v[48:49], v[4:5], v[60:61]
	v_pk_mul_f32 v[54:55], v[2:3], v[58:59]
	v_pk_mul_f32 v[52:53], v[0:1], v[56:57]
	v_pk_mul_f32 v[58:59], v[14:15], v[70:71]
	v_pk_mul_f32 v[56:57], v[12:13], v[68:69]
	v_pk_mul_f32 v[62:63], v[10:11], v[64:65]
	v_pk_mul_f32 v[60:61], v[8:9], v[72:73]
	global_store_dwordx4 v[66:67], v[48:51], off nt
	global_store_dwordx4 v[66:67], v[52:55], off offset:16 nt
	global_store_dwordx4 v[66:67], v[56:59], off offset:512 nt
	global_store_dwordx4 v[66:67], v[60:63], off offset:528 nt
	global_load_dword v48, v[112:113], off offset:576 sc1
	v_lshlrev_b64 v[50:51], 12, v[204:205]
	v_lshl_add_u64 v[50:51], s[20:21], 0, v[50:51]
	v_lshl_add_u64 v[50:51], v[50:51], 0, v[144:145]
	s_waitcnt vmcnt(0)
	v_fmamk_f32 v48, v48, 0x3a800000, v226
	v_rsq_f32_e32 v48, v48
	s_nop 0
	v_pk_mul_f32 v[44:45], v[44:45], v[48:49] op_sel_hi:[1,0]
	v_pk_mul_f32 v[46:47], v[46:47], v[48:49] op_sel_hi:[1,0]
	v_pk_mul_f32 v[40:41], v[40:41], v[48:49] op_sel_hi:[1,0]
	v_pk_mul_f32 v[42:43], v[42:43], v[48:49] op_sel_hi:[1,0]
	v_pk_mul_f32 v[52:53], v[36:37], v[48:49] op_sel_hi:[1,0]
	v_pk_mul_f32 v[54:55], v[38:39], v[48:49] op_sel_hi:[1,0]
	v_pk_mul_f32 v[56:57], v[32:33], v[48:49] op_sel_hi:[1,0]
	v_pk_mul_f32 v[48:49], v[34:35], v[48:49] op_sel_hi:[1,0]
	v_pk_mul_f32 v[34:35], v[6:7], v[46:47]
	v_pk_mul_f32 v[32:33], v[4:5], v[44:45]
	v_pk_mul_f32 v[38:39], v[2:3], v[42:43]
	v_pk_mul_f32 v[36:37], v[0:1], v[40:41]
	v_pk_mul_f32 v[42:43], v[14:15], v[54:55]
	v_pk_mul_f32 v[40:41], v[12:13], v[52:53]
	v_pk_mul_f32 v[46:47], v[10:11], v[48:49]
	v_pk_mul_f32 v[44:45], v[8:9], v[56:57]
	global_store_dwordx4 v[50:51], v[32:35], off nt
	global_store_dwordx4 v[50:51], v[36:39], off offset:16 nt
	global_store_dwordx4 v[50:51], v[40:43], off offset:512 nt
	global_store_dwordx4 v[50:51], v[44:47], off offset:528 nt
	global_load_dword v32, v[112:113], off offset:640 sc1
	v_lshlrev_b64 v[34:35], 12, v[202:203]
	v_lshl_add_u64 v[34:35], s[20:21], 0, v[34:35]
	v_lshl_add_u64 v[40:41], v[34:35], 0, v[144:145]
	s_waitcnt vmcnt(0)
	v_fmamk_f32 v32, v32, 0x3a800000, v226
	v_rsq_f32_e32 v32, v32
	s_nop 0
	v_pk_mul_f32 v[28:29], v[28:29], v[32:33] op_sel_hi:[1,0]
	v_pk_mul_f32 v[30:31], v[30:31], v[32:33] op_sel_hi:[1,0]
	v_pk_mul_f32 v[34:35], v[24:25], v[32:33] op_sel_hi:[1,0]
	v_pk_mul_f32 v[36:37], v[26:27], v[32:33] op_sel_hi:[1,0]
	v_pk_mul_f32 v[38:39], v[140:141], v[32:33] op_sel_hi:[1,0]
	v_pk_mul_f32 v[42:43], v[142:143], v[32:33] op_sel_hi:[1,0]
	v_pk_mul_f32 v[44:45], v[136:137], v[32:33] op_sel_hi:[1,0]
	v_pk_mul_f32 v[46:47], v[138:139], v[32:33] op_sel_hi:[1,0]
	v_pk_mul_f32 v[26:27], v[6:7], v[30:31]
	v_pk_mul_f32 v[24:25], v[4:5], v[28:29]
	v_pk_mul_f32 v[30:31], v[2:3], v[36:37]
	v_pk_mul_f32 v[28:29], v[0:1], v[34:35]
	v_pk_mul_f32 v[34:35], v[14:15], v[42:43]
	v_pk_mul_f32 v[32:33], v[12:13], v[38:39]
	v_pk_mul_f32 v[38:39], v[10:11], v[46:47]
	v_pk_mul_f32 v[36:37], v[8:9], v[44:45]
	global_store_dwordx4 v[40:41], v[24:27], off nt
	global_store_dwordx4 v[40:41], v[28:31], off offset:16 nt
	global_store_dwordx4 v[40:41], v[32:35], off offset:512 nt
	global_store_dwordx4 v[40:41], v[36:39], off offset:528 nt
	global_load_dword v26, v[112:113], off offset:704 sc1
	v_lshlrev_b64 v[24:25], 12, v[200:201]
	v_lshl_add_u64 v[24:25], s[20:21], 0, v[24:25]
	v_lshl_add_u64 v[24:25], v[24:25], 0, v[144:145]
	s_waitcnt vmcnt(0)
	v_fmamk_f32 v26, v26, 0x3a800000, v226
	v_rsq_f32_e32 v26, v26
	s_nop 0
	v_pk_mul_f32 v[16:17], v[16:17], v[26:27] op_sel_hi:[1,0]
	v_pk_mul_f32 v[18:19], v[18:19], v[26:27] op_sel_hi:[1,0]
	v_pk_mul_f32 v[20:21], v[20:21], v[26:27] op_sel_hi:[1,0]
	v_pk_mul_f32 v[22:23], v[22:23], v[26:27] op_sel_hi:[1,0]
	v_pk_mul_f32 v[28:29], v[132:133], v[26:27] op_sel_hi:[1,0]
	v_pk_mul_f32 v[30:31], v[128:129], v[26:27] op_sel_hi:[1,0]
	v_pk_mul_f32 v[32:33], v[134:135], v[26:27] op_sel_hi:[1,0]
	v_pk_mul_f32 v[26:27], v[130:131], v[26:27] op_sel_hi:[1,0]
	v_pk_mul_f32 v[6:7], v[6:7], v[18:19]
	v_pk_mul_f32 v[4:5], v[4:5], v[16:17]
	v_pk_mul_f32 v[2:3], v[2:3], v[22:23]
	v_pk_mul_f32 v[0:1], v[0:1], v[20:21]
	v_pk_mul_f32 v[14:15], v[14:15], v[30:31]
	v_pk_mul_f32 v[12:13], v[12:13], v[28:29]
	v_pk_mul_f32 v[10:11], v[10:11], v[26:27]
	v_pk_mul_f32 v[8:9], v[8:9], v[32:33]
	global_store_dwordx4 v[24:25], v[4:7], off nt
	global_store_dwordx4 v[24:25], v[0:3], off offset:16 nt
	global_store_dwordx4 v[24:25], v[12:15], off offset:512 nt
	global_store_dwordx4 v[24:25], v[8:11], off offset:528 nt
	s_cbranch_vccnz .LBB0_887
	s_andn2_b64 vcc, exec, s[36:37]
	s_cbranch_vccnz .LBB0_886
	s_barrier
	s_branch .LBB0_886
